# attention final P.V: eight V-fragment LDS reads issued back to back, each MFMA waits for its own fragment
# speedup vs baseline: 1.0070x; 1.0005x over previous
.LBB0_898:
	s_add_i32 s9, s3, -1
	s_min_u32 s9, s9, s2
	s_lshl_b32 s9, s9, 6
	s_waitcnt vmcnt(1)
	ds_write_b128 v142, v[112:115] offset:16384
	s_waitcnt vmcnt(0)
	ds_write_b128 v142, v[116:119] offset:24576
	v_mad_u64_u32 v[64:65], s[18:19], s9, v237, v[132:133]
	global_load_dwordx4 v[120:123], v[64:65], off offset:2048
	global_load_dwordx4 v[124:127], v[136:137], off offset:-128
	ds_read_b128 v[64:67], v144 offset:8192
	ds_read_b128 v[68:71], v144 offset:12288
	ds_read_b128 v[72:75], v141 offset:8192
	ds_read_b128 v[76:79], v141 offset:12288
	v_exp_f32_e32 v151, v48
	v_exp_f32_e32 v152, v49
	s_waitcnt lgkmcnt(3)
	v_mfma_f32_32x32x16_bf16 v[16:31], v[64:67], v[80:83], v[16:31]
	v_exp_f32_e32 v153, v50
	v_exp_f32_e32 v154, v51
	ds_read_b128 v[48:51], v140 offset:8192
	ds_read_b128 v[64:67], v140 offset:12288
	v_exp_f32_e32 v155, v52
	s_waitcnt lgkmcnt(4)
	v_mfma_f32_32x32x16_bf16 v[0:15], v[68:71], v[80:83], v[0:15]
	v_exp_f32_e32 v156, v53
	v_exp_f32_e32 v159, v54
	v_exp_f32_e32 v160, v55
	v_exp_f32_e32 v162, v57
	s_waitcnt lgkmcnt(3)
	v_mfma_f32_32x32x16_bf16 v[16:31], v[72:75], v[84:87], v[16:31]
	ds_read_b128 v[68:71], v139 offset:8192
	ds_read_b128 v[80:83], v139 offset:12288
	v_add_f32_e32 v157, v155, v151
	v_add_f32_e32 v158, v156, v152
	ds_read_b128 v[52:55], v164
	ds_read_b128 v[72:75], v164 offset:4096
	v_add_f32_e32 v161, v159, v153
	s_waitcnt lgkmcnt(6)
	v_mfma_f32_32x32x16_bf16 v[0:15], v[76:79], v[84:87], v[0:15]
	v_exp_f32_e32 v77, v56
	v_add_f32_e32 v76, v160, v154
	v_exp_f32_e32 v62, v62
	ds_read_b128 v[112:115], v165
	ds_read_b128 v[116:119], v165 offset:4096
	v_cvt_pk_bf16_f32 v56, v151, v152
	s_waitcnt lgkmcnt(7)
	v_mfma_f32_32x32x16_bf16 v[16:31], v[48:51], v[88:91], v[16:31]
	v_exp_f32_e32 v49, v58
	v_exp_f32_e32 v50, v59
	v_add_f32_e32 v48, v77, v157
	v_add_f32_e32 v51, v162, v158
	v_add_f32_e32 v78, v49, v161
	v_add_f32_e32 v76, v50, v76
	s_waitcnt lgkmcnt(6)
	v_mfma_f32_32x32x16_bf16 v[0:15], v[64:67], v[88:91], v[0:15]
	v_exp_f32_e32 v60, v60
	v_add_f32_e32 v151, v62, v78
	v_exp_f32_e32 v61, v61
	v_exp_f32_e32 v63, v63
	v_cvt_pk_bf16_f32 v59, v159, v160
	v_exp_f32_e32 v160, v33
	s_waitcnt lgkmcnt(5)
	v_mfma_f32_32x32x16_bf16 v[16:31], v[68:71], v[92:95], v[16:31]
	v_cvt_pk_bf16_f32 v57, v153, v154
	v_cvt_pk_bf16_f32 v58, v155, v156
	v_add_f32_e32 v48, v60, v48
	v_add_f32_e32 v51, v61, v51
	v_cvt_pk_bf16_f32 v49, v49, v50
	s_waitcnt lgkmcnt(4)
	v_mfma_f32_32x32x16_bf16 v[0:15], v[80:83], v[92:95], v[0:15]
	v_exp_f32_e32 v95, v32
	v_add_f32_e32 v32, v63, v76
	v_add_f32_e32 v163, v160, v51
	v_add_f32_e32 v161, v95, v48
	v_cvt_pk_bf16_f32 v48, v77, v162
	v_cvt_pk_bf16_f32 v51, v62, v63
	s_waitcnt lgkmcnt(3)
	v_mfma_f32_32x32x16_bf16 v[78:93], v[52:55], v[96:99], 0
	v_cvt_pk_bf16_f32 v50, v60, v61
	v_exp_f32_e32 v60, v34
	v_exp_f32_e32 v61, v35
	v_exp_f32_e32 v36, v36
	v_exp_f32_e32 v37, v37
	v_exp_f32_e32 v38, v38
	v_exp_f32_e32 v39, v39
	s_waitcnt lgkmcnt(2)
	v_mfma_f32_32x32x16_bf16 v[62:77], v[72:75], v[96:99], 0
	ds_read_b128 v[52:55], v166
	ds_read_b128 v[152:155], v166 offset:4096
	v_add_f32_e32 v151, v60, v151
	v_add_f32_e32 v162, v61, v32
	s_waitcnt lgkmcnt(3)
	v_mfma_f32_32x32x16_bf16 v[78:93], v[112:115], v[100:103], v[78:93]
	v_add_f32_e32 v112, v36, v161
	v_add_f32_e32 v113, v37, v163
	v_add_f32_e32 v114, v38, v151
	v_exp_f32_e32 v115, v40
	v_add_f32_e32 v40, v39, v162
	ds_read_b128 v[32:35], v167
	ds_read_b128 v[156:159], v167 offset:4096
	s_waitcnt lgkmcnt(4)
	v_mfma_f32_32x32x16_bf16 v[62:77], v[116:119], v[100:103], v[62:77]
	v_exp_f32_e32 v116, v41
	v_add_f32_e32 v41, v115, v112
	s_min_u32 s9, s3, s2
	s_lshl_b32 s9, s9, 6
	v_add_f32_e32 v112, v116, v113
	s_waitcnt lgkmcnt(3)
	v_mfma_f32_32x32x16_bf16 v[78:93], v[52:55], v[104:107], v[78:93]
	v_cvt_pk_bf16_f32 v54, v36, v37
	v_exp_f32_e32 v37, v42
	v_cvt_pk_bf16_f32 v55, v38, v39
	v_exp_f32_e32 v38, v43
	v_exp_f32_e32 v39, v44
	v_exp_f32_e32 v44, v45
	v_exp_f32_e32 v45, v46
	v_exp_f32_e32 v46, v47
	v_cvt_pk_bf16_f32 v52, v95, v160
	v_cvt_pk_bf16_f32 v53, v60, v61
	v_add_f32_e32 v36, v37, v114
	v_add_f32_e32 v43, v38, v40
	v_add_f32_e32 v40, v39, v41
	v_add_f32_e32 v42, v44, v112
	v_add_f32_e32 v41, v45, v36
	v_add_f32_e32 v43, v46, v43
	v_cvt_pk_bf16_f32 v36, v115, v116
	v_cvt_pk_bf16_f32 v37, v37, v38
	v_cvt_pk_bf16_f32 v38, v39, v44
	v_cvt_pk_bf16_f32 v39, v45, v46
	s_waitcnt lgkmcnt(1)
	v_mfma_f32_32x32x16_bf16 v[78:93], v[32:35], v[108:111], v[78:93]
	s_waitcnt lgkmcnt(0)
	s_barrier
	v_mad_u64_u32 v[32:33], s[18:19], s9, v237, v[132:133]
	global_load_dwordx4 v[112:115], v[32:33], off offset:2048
	global_load_dwordx4 v[116:119], v[136:137], off
	v_add_f32_e64 v32, v40, v42
	v_add_f32_e64 v33, v41, v43
	s_waitcnt vmcnt(3)
	ds_write_b128 v142, v[120:123]
	s_waitcnt vmcnt(2)
	ds_write_b128 v142, v[124:127] offset:8192
	v_mfma_f32_32x32x16_bf16 v[62:77], v[152:155], v[104:107], v[62:77]
	v_add_f32_e32 v32, v32, v33
	v_add_f32_e32 v150, v150, v32
	s_waitcnt lgkmcnt(2)
	v_mfma_f32_32x32x16_bf16 v[62:77], v[156:159], v[108:111], v[62:77]
	ds_read_b128 v[32:35], v144 offset:24576
	ds_read_b128 v[40:43], v144 offset:28672
	ds_read_b128 v[44:47], v141 offset:24576
	ds_read_b128 v[120:123], v141 offset:28672
	v_exp_f32_e32 v60, v78
	s_waitcnt lgkmcnt(3)
	v_mfma_f32_32x32x16_bf16 v[16:31], v[32:35], v[56:59], v[16:31]
	v_exp_f32_e32 v61, v79
	v_exp_f32_e32 v95, v80
	v_exp_f32_e32 v81, v81
	ds_read_b128 v[152:155], v140 offset:24576
	ds_read_b128 v[156:159], v140 offset:28672
	s_waitcnt lgkmcnt(4)
	v_mfma_f32_32x32x16_bf16 v[0:15], v[40:43], v[56:59], v[0:15]
	v_exp_f32_e32 v82, v82
	v_exp_f32_e32 v83, v83
	v_add_f32_e32 v78, v82, v60
	v_add_f32_e32 v79, v83, v61
	s_waitcnt lgkmcnt(2)
	v_mfma_f32_32x32x16_bf16 v[0:15], v[120:123], v[48:51], v[0:15]
	ds_read_b128 v[56:59], v139 offset:24576
	ds_read_b128 v[160:163], v139 offset:28672
	ds_read_b128 v[40:43], v164 offset:16384
	ds_read_b128 v[32:35], v164 offset:20480
	v_cvt_pk_bf16_f32 v82, v82, v83
	v_exp_f32_e32 v151, v62
	v_exp_f32_e32 v64, v64
	v_exp_f32_e32 v65, v65
	v_mfma_f32_32x32x16_bf16 v[16:31], v[44:47], v[48:51], v[16:31]
	v_exp_f32_e32 v44, v84
	v_exp_f32_e32 v45, v85
	v_exp_f32_e32 v84, v86
	v_exp_f32_e32 v85, v87
	v_add_f32_e32 v46, v44, v95
	v_add_f32_e32 v47, v45, v81
	v_add_f32_e32 v48, v84, v78
	s_waitcnt lgkmcnt(4)
	v_mfma_f32_32x32x16_bf16 v[0:15], v[156:159], v[52:55], v[0:15]
	v_add_f32_e32 v49, v85, v79
	v_exp_f32_e32 v78, v88
	v_exp_f32_e32 v79, v89
	v_exp_f32_e32 v87, v92
	v_cvt_pk_bf16_f32 v83, v44, v45
	v_exp_f32_e32 v44, v90
	v_mfma_f32_32x32x16_bf16 v[16:31], v[152:155], v[52:55], v[16:31]
	v_exp_f32_e32 v45, v91
	v_exp_f32_e32 v92, v93
	v_add_f32_e32 v46, v78, v46
	v_add_f32_e32 v47, v79, v47
	ds_read_b128 v[124:127], v165 offset:16384
	ds_read_b128 v[120:123], v165 offset:20480
	s_waitcnt lgkmcnt(4)
	v_mfma_f32_32x32x16_bf16 v[0:15], v[160:163], v[36:39], v[0:15]
	v_exp_f32_e32 v160, v63
	v_cvt_pk_bf16_f32 v80, v60, v61
	v_cvt_pk_bf16_f32 v81, v95, v81
	v_add_f32_e32 v48, v44, v48
	v_add_f32_e32 v49, v45, v49
	v_add_f32_e32 v46, v87, v46
	v_add_f32_e32 v47, v92, v47
	v_mfma_f32_32x32x16_bf16 v[16:31], v[56:59], v[36:39], v[16:31]
	v_add_f32_e32 v161, v151, v48
	v_add_f32_e32 v162, v160, v49
	v_cvt_pk_bf16_f32 v84, v84, v85
	v_cvt_pk_bf16_f32 v85, v78, v79
	v_cvt_pk_bf16_f32 v86, v44, v45
	v_add_f32_e32 v78, v64, v46
	v_add_f32_e32 v79, v65, v47
	s_waitcnt lgkmcnt(3)
	v_mfma_f32_32x32x16_bf16 v[48:63], v[40:43], v[96:99], 0
	ds_read_b128 v[88:91], v166 offset:16384
	ds_read_b128 v[152:155], v166 offset:20480
	v_exp_f32_e32 v66, v66
	v_exp_f32_e32 v67, v67
	v_exp_f32_e32 v68, v68
	v_exp_f32_e32 v69, v69
	v_cvt_pk_bf16_f32 v87, v87, v92
	s_waitcnt lgkmcnt(4)
	v_mfma_f32_32x32x16_bf16 v[32:47], v[32:35], v[96:99], 0
	ds_read_b128 v[156:159], v167 offset:16384
	ds_read_b128 v[92:95], v167 offset:20480
	v_add_f32_e32 v161, v66, v161
	v_add_f32_e32 v162, v67, v162
	v_add_f32_e32 v78, v68, v78
	v_add_f32_e32 v79, v69, v79
	s_waitcnt lgkmcnt(5)
	v_mfma_f32_32x32x16_bf16 v[48:63], v[124:127], v[100:103], v[48:63]
	v_exp_f32_e32 v70, v70
	v_exp_f32_e32 v71, v71
	s_add_i32 s9, s3, 2
	s_add_i32 s3, s3, -2
	v_lshl_add_u64 v[136:137], v[136:137], 0, s[22:23]
	s_waitcnt lgkmcnt(4)
	v_mfma_f32_32x32x16_bf16 v[32:47], v[120:123], v[100:103], v[32:47]
	v_add_f32_e32 v120, v70, v161
	v_add_f32_e32 v121, v71, v162
	s_cmp_lt_u32 s3, s2
	s_mov_b32 s3, s9
	s_waitcnt lgkmcnt(3)
	v_mfma_f32_32x32x16_bf16 v[48:63], v[88:91], v[104:107], v[48:63]
	v_cvt_pk_bf16_f32 v91, v68, v69
	v_exp_f32_e32 v68, v72
	v_exp_f32_e32 v69, v73
	v_exp_f32_e32 v72, v74
	v_exp_f32_e32 v73, v75
	v_exp_f32_e32 v74, v76
	v_exp_f32_e32 v75, v77
	s_waitcnt lgkmcnt(2)
	v_mfma_f32_32x32x16_bf16 v[32:47], v[152:155], v[104:107], v[32:47]
	v_cvt_pk_bf16_f32 v88, v151, v160
	v_cvt_pk_bf16_f32 v89, v64, v65
	v_cvt_pk_bf16_f32 v90, v66, v67
	v_add_f32_e32 v65, v68, v78
	v_add_f32_e32 v67, v69, v79
	s_waitcnt lgkmcnt(1)
	v_mfma_f32_32x32x16_bf16 v[48:63], v[156:159], v[108:111], v[48:63]
	v_add_f32_e32 v64, v72, v120
	v_add_f32_e32 v66, v73, v121
	v_add_f32_e32 v65, v74, v65
	v_add_f32_e32 v67, v75, v67
	s_waitcnt lgkmcnt(0)
	v_mfma_f32_32x32x16_bf16 v[32:47], v[92:95], v[108:111], v[32:47]
	v_cvt_pk_bf16_f32 v92, v70, v71
	v_cvt_pk_bf16_f32 v93, v68, v69
	v_cvt_pk_bf16_f32 v94, v72, v73
	v_cvt_pk_bf16_f32 v95, v74, v75
	v_add_f32_e64 v64, v64, v66
	v_add_f32_e64 v65, v65, v67
	s_waitcnt lgkmcnt(0)
	s_barrier
	v_add_f32_e32 v64, v64, v65
	v_add_f32_e32 v150, v150, v64
	s_cbranch_scc1 .LBB0_898
	v_ashrrev_i32_e32 v64, 1, v129
	v_and_or_b32 v132, v64, s88, v148
	v_lshlrev_b32_e32 v176, 4, v138
	s_waitcnt vmcnt(1)
	ds_write_b128 v142, v[112:115] offset:16384
	s_waitcnt vmcnt(0)
	ds_write_b128 v142, v[116:119] offset:24576
	ds_read_b128 v[124:127], v172 offset:32768
	ds_read_b128 v[120:123], v172 offset:40960
	ds_read_b128 v[116:119], v172 offset:49152
	ds_read_b128 v[112:115], v172 offset:57344
	v_ashrrev_i32_e32 v133, 31, v132
	ds_read_b128 v[128:131], v144 offset:8192
	ds_read_b128 v[134:137], v144 offset:12288
	ds_read_b128 v[146:149], v141 offset:8192
	ds_read_b128 v[152:155], v141 offset:12288
	v_exp_f32_e32 v138, v48
	v_exp_f32_e32 v142, v49
	s_waitcnt lgkmcnt(3)
	v_mfma_f32_32x32x16_bf16 v[16:31], v[128:131], v[80:83], v[16:31]
	v_exp_f32_e32 v151, v50
	v_add_f32_e32 v143, 0, v138
	v_add_f32_e32 v145, 0, v142
	v_exp_f32_e32 v156, v51
	ds_read_b128 v[48:51], v140 offset:8192
	ds_read_b128 v[128:131], v140 offset:12288
	v_exp_f32_e32 v52, v52
	s_waitcnt lgkmcnt(4)
	v_mfma_f32_32x32x16_bf16 v[0:15], v[134:137], v[80:83], v[0:15]
	v_exp_f32_e32 v53, v53
	v_exp_f32_e32 v54, v54
	v_exp_f32_e32 v55, v55
	v_add_f32_e32 v157, 0, v151
	v_add_f32_e32 v158, 0, v156
	v_add_f32_e32 v143, v52, v143
	s_waitcnt lgkmcnt(3)
	v_mfma_f32_32x32x16_bf16 v[16:31], v[146:149], v[84:87], v[16:31]
	v_add_f32_e32 v145, v53, v145
	v_add_f32_e32 v146, v54, v157
	ds_read_b128 v[80:83], v139 offset:8192
	ds_read_b128 v[134:137], v139 offset:12288
	v_exp_f32_e32 v56, v56
	v_exp_f32_e32 v57, v57
	v_exp_f32_e32 v58, v58
	s_waitcnt lgkmcnt(4)
	v_mfma_f32_32x32x16_bf16 v[0:15], v[152:155], v[84:87], v[0:15]
	v_add_f32_e32 v84, v55, v158
	v_exp_f32_e32 v59, v59
	v_exp_f32_e32 v60, v60
	v_exp_f32_e32 v32, v32
	v_exp_f32_e32 v33, v33
	v_exp_f32_e32 v34, v34
	s_waitcnt lgkmcnt(3)
	v_mfma_f32_32x32x16_bf16 v[16:31], v[48:51], v[88:91], v[16:31]
	v_cvt_pk_bf16_f32 v51, v54, v55
	v_exp_f32_e32 v54, v61
	v_exp_f32_e32 v55, v62
	v_exp_f32_e32 v61, v63
	v_exp_f32_e32 v35, v35
	v_add_f32_e32 v85, v56, v143
	v_add_f32_e32 v86, v57, v145
	v_add_f32_e32 v87, v58, v146
	v_add_f32_e32 v84, v59, v84
	v_cvt_pk_bf16_f32 v48, v138, v142
	v_cvt_pk_bf16_f32 v49, v151, v156
	v_cvt_pk_bf16_f32 v50, v52, v53
	v_add_f32_e32 v52, v60, v85
	v_add_f32_e32 v53, v54, v86
	v_add_f32_e32 v62, v55, v87
	v_add_f32_e32 v63, v61, v84
	v_exp_f32_e32 v36, v36
	v_exp_f32_e32 v37, v37
	v_exp_f32_e32 v38, v38
	v_exp_f32_e32 v39, v39
	s_waitcnt lgkmcnt(1)
	v_mfma_f32_32x32x16_bf16 v[16:31], v[80:83], v[92:95], v[16:31]
	v_add_f32_e32 v80, v32, v52
	v_add_f32_e32 v81, v33, v53
	v_cvt_pk_bf16_f32 v52, v56, v57
	v_cvt_pk_bf16_f32 v53, v58, v59
	v_cvt_pk_bf16_f32 v54, v60, v54
	v_cvt_pk_bf16_f32 v55, v55, v61
	v_add_f32_e32 v56, v34, v62
	v_add_f32_e32 v57, v35, v63
	v_exp_f32_e32 v40, v40
	v_add_f32_e32 v58, v36, v80
	v_add_f32_e32 v59, v37, v81
	v_add_f32_e32 v56, v38, v56
	v_exp_f32_e32 v41, v41
	v_add_f32_e32 v57, v39, v57
	v_mfma_f32_32x32x16_bf16 v[0:15], v[128:131], v[88:91], v[0:15]
	v_cvt_pk_bf16_f32 v32, v32, v33
	v_cvt_pk_bf16_f32 v33, v34, v35
	v_cvt_pk_bf16_f32 v34, v36, v37
	v_exp_f32_e32 v37, v42
	v_cvt_pk_bf16_f32 v35, v38, v39
	v_exp_f32_e32 v38, v43
	v_exp_f32_e32 v39, v44
	v_exp_f32_e32 v43, v45
	v_exp_f32_e32 v44, v46
	v_exp_f32_e32 v45, v47
	v_add_f32_e32 v58, v40, v58
	v_add_f32_e32 v59, v41, v59
	v_add_f32_e32 v36, v37, v56
	v_add_f32_e32 v42, v38, v57
	v_add_f32_e32 v56, v39, v58
	v_add_f32_e32 v58, v43, v59
	s_waitcnt lgkmcnt(0)
	v_mfma_f32_32x32x16_bf16 v[0:15], v[134:137], v[92:95], v[0:15]
	v_add_f32_e32 v57, v44, v36
	v_add_f32_e32 v59, v45, v42
	v_cvt_pk_bf16_f32 v36, v40, v41
	v_cvt_pk_bf16_f32 v37, v37, v38
	v_cvt_pk_bf16_f32 v38, v39, v43
	v_cvt_pk_bf16_f32 v39, v44, v45
	s_waitcnt lgkmcnt(0)
	s_barrier
	ds_read_b128 v[178:181], v144 offset:24576
	ds_read_b128 v[182:185], v144 offset:28672
	ds_read_b128 v[186:189], v141 offset:24576
	ds_read_b128 v[190:193], v141 offset:28672
	ds_read_b128 v[194:197], v140 offset:24576
	ds_read_b128 v[198:201], v140 offset:28672
	ds_read_b128 v[202:205], v139 offset:24576
	ds_read_b128 v[206:209], v139 offset:28672
	s_waitcnt lgkmcnt(7)
	v_mfma_f32_32x32x16_bf16 v[16:31], v[178:181], v[48:51], v[16:31]
	s_waitcnt lgkmcnt(6)
	v_mfma_f32_32x32x16_bf16 v[0:15], v[182:185], v[48:51], v[0:15]
	s_waitcnt lgkmcnt(5)
	v_mfma_f32_32x32x16_bf16 v[16:31], v[186:189], v[52:55], v[16:31]
	s_waitcnt lgkmcnt(4)
	v_mfma_f32_32x32x16_bf16 v[0:15], v[190:193], v[52:55], v[0:15]
	s_waitcnt lgkmcnt(3)
	v_mfma_f32_32x32x16_bf16 v[16:31], v[194:197], v[32:35], v[16:31]
	s_waitcnt lgkmcnt(2)
	v_mfma_f32_32x32x16_bf16 v[0:15], v[198:201], v[32:35], v[0:15]
	s_waitcnt lgkmcnt(1)
	v_mfma_f32_32x32x16_bf16 v[16:31], v[202:205], v[36:39], v[16:31]
	v_add_f32_e64 v32, v56, v58
	v_add_f32_e64 v33, v57, v59
	v_add_f32_e32 v32, v32, v33
	v_add_f32_e32 v32, v150, v32
	v_mov_b32_e32 v33, v32
	s_nop 1
	v_permlane32_swap_b32_e32 v32, v33
	v_add_f32_e32 v32, v32, v33
	v_div_scale_f32 v33, s[2:3], v32, v32, 1.0
	v_rcp_f32_e32 v34, v33
	s_waitcnt lgkmcnt(0)
	v_mfma_f32_32x32x16_bf16 v[0:15], v[206:209], v[36:39], v[0:15]
	s_waitcnt vmcnt(11)
	v_mov_b32_e32 v40, v127
	s_nop 1
	v_permlane32_swap_b32_e32 v125, v40
	v_fma_f32 v35, -v33, v34, 1.0
	v_fmac_f32_e32 v34, v35, v34
	v_div_scale_f32 v35, vcc, 1.0, v32, 1.0
	v_mul_f32_e32 v36, v35, v34
	v_fma_f32 v37, -v33, v36, v35
	v_fmac_f32_e32 v36, v37, v34
	v_fma_f32 v33, -v33, v36, v35
	v_div_fmas_f32 v33, v33, v34, v36
	v_mov_b32_e32 v35, v126
	v_div_fixup_f32 v34, v33, v32, 1.0
	s_nop 0
	v_permlane32_swap_b32_e32 v124, v35
	v_lshlrev_b32_e32 v38, 16, v124
	v_and_b32_e32 v39, 0xffff0000, v124
	v_mul_f32_e32 v16, v16, v34
	v_mul_f32_e32 v17, v17, v34
	v_mul_f32_e32 v18, v18, v34
	v_mul_f32_e32 v19, v19, v34
	v_mul_f32_e32 v16, v16, v38
	v_mul_f32_e32 v17, v17, v39
	v_lshlrev_b32_e32 v38, 16, v125
	v_and_b32_e32 v39, 0xffff0000, v125
	v_mul_f32_e32 v18, v18, v38
	v_mul_f32_e32 v19, v19, v39
	v_cvt_pk_bf16_f32 v16, v16, v17
	v_cvt_pk_bf16_f32 v17, v18, v19
	v_lshlrev_b32_e32 v18, 16, v35
	v_and_b32_e32 v19, 0xffff0000, v35
	v_mul_f32_e32 v20, v20, v34
	v_mul_f32_e32 v21, v21, v34
	v_mul_f32_e32 v22, v22, v34
	v_mul_f32_e32 v23, v23, v34
	v_mul_f32_e32 v18, v20, v18
	v_mul_f32_e32 v19, v21, v19
	v_lshlrev_b32_e32 v20, 16, v40
	v_and_b32_e32 v21, 0xffff0000, v40
	v_lshlrev_b64 v[32:33], 11, v[132:133]
	v_mul_f32_e32 v20, v22, v20
	v_mul_f32_e32 v21, v23, v21
	v_lshl_add_u64 v[32:33], s[6:7], 0, v[32:33]
	v_cvt_pk_bf16_f32 v18, v18, v19
	v_cvt_pk_bf16_f32 v19, v20, v21
	s_waitcnt vmcnt(10)
	v_mov_b32_e32 v22, v122
	v_lshl_add_u64 v[36:37], v[32:33], 0, v[176:177]
	v_permlane32_swap_b32_e32 v16, v18
	v_permlane32_swap_b32_e32 v17, v19
	v_permlane32_swap_b32_e32 v120, v22
	v_mov_b32_e32 v23, v123
	global_store_dwordx4 v[36:37], v[16:19], off offset:512
	s_nop 0
	v_permlane32_swap_b32_e32 v121, v23
	v_lshlrev_b32_e32 v16, 16, v120
	v_and_b32_e32 v17, 0xffff0000, v120
	v_mul_f32_e32 v18, v24, v34
	v_mul_f32_e32 v19, v25, v34
	v_mul_f32_e32 v20, v26, v34
	v_mul_f32_e32 v21, v27, v34
	v_mul_f32_e32 v16, v18, v16
	v_mul_f32_e32 v17, v19, v17
	v_lshlrev_b32_e32 v18, 16, v121
	v_and_b32_e32 v19, 0xffff0000, v121
	v_mul_f32_e32 v18, v20, v18
	v_mul_f32_e32 v19, v21, v19
	v_cvt_pk_bf16_f32 v16, v16, v17
	v_cvt_pk_bf16_f32 v17, v18, v19
	v_lshlrev_b32_e32 v18, 16, v22
	v_and_b32_e32 v19, 0xffff0000, v22
	v_mul_f32_e32 v20, v28, v34
	v_mul_f32_e32 v21, v29, v34
	v_mul_f32_e32 v0, v0, v34
	v_mul_f32_e32 v1, v1, v34
	v_mul_f32_e32 v18, v20, v18
	v_mul_f32_e32 v19, v21, v19
	v_lshlrev_b32_e32 v20, 16, v23
	v_and_b32_e32 v21, 0xffff0000, v23
	v_mul_f32_e32 v22, v30, v34
	v_mul_f32_e32 v23, v31, v34
	v_cvt_pk_bf16_f32 v18, v18, v19
	v_mul_f32_e32 v20, v22, v20
	v_mul_f32_e32 v21, v23, v21
	s_nop 0
	v_permlane32_swap_b32_e32 v16, v18
	v_cvt_pk_bf16_f32 v19, v20, v21
	s_nop 1
	v_permlane32_swap_b32_e32 v17, v19
	global_store_dwordx4 v[36:37], v[16:19], off offset:544
	v_mul_f32_e32 v2, v2, v34
	v_mul_f32_e32 v3, v3, v34
	v_mul_f32_e32 v4, v4, v34
	v_mul_f32_e32 v5, v5, v34
	s_waitcnt vmcnt(11)
	v_mov_b32_e32 v18, v118
	s_nop 1
	v_permlane32_swap_b32_e32 v116, v18
	v_mov_b32_e32 v19, v119
	s_nop 1
	v_permlane32_swap_b32_e32 v117, v19
	v_lshlrev_b32_e32 v16, 16, v116
	v_and_b32_e32 v17, 0xffff0000, v116
	v_mul_f32_e32 v0, v0, v16
	v_mul_f32_e32 v1, v1, v17
	v_lshlrev_b32_e32 v16, 16, v117
	v_and_b32_e32 v17, 0xffff0000, v117
	v_mul_f32_e32 v2, v2, v16
	v_mul_f32_e32 v3, v3, v17
	v_cvt_pk_bf16_f32 v0, v0, v1
	v_cvt_pk_bf16_f32 v1, v2, v3
	v_lshlrev_b32_e32 v2, 16, v18
	v_and_b32_e32 v3, 0xffff0000, v18
	v_mul_f32_e32 v2, v4, v2
	v_mul_f32_e32 v3, v5, v3
	v_lshlrev_b32_e32 v4, 16, v19
	v_and_b32_e32 v5, 0xffff0000, v19
	v_mul_f32_e32 v6, v6, v34
	v_mul_f32_e32 v7, v7, v34
	v_cvt_pk_bf16_f32 v2, v2, v3
	v_mul_f32_e32 v4, v6, v4
	v_mul_f32_e32 v5, v7, v5
	s_waitcnt vmcnt(10)
	v_mov_b32_e32 v6, v114
	v_cvt_pk_bf16_f32 v3, v4, v5
	v_permlane32_swap_b32_e32 v0, v2
	s_nop 0
	v_permlane32_swap_b32_e32 v1, v3
	v_permlane32_swap_b32_e32 v112, v6
	v_mov_b32_e32 v7, v115
	global_store_dwordx4 v[36:37], v[0:3], off offset:576
	s_nop 0
	v_permlane32_swap_b32_e32 v113, v7
	v_lshlrev_b32_e32 v0, 16, v112
	v_and_b32_e32 v1, 0xffff0000, v112
	v_mul_f32_e32 v2, v8, v34
	v_mul_f32_e32 v3, v9, v34
	v_mul_f32_e32 v4, v10, v34
	v_mul_f32_e32 v5, v11, v34
	v_mul_f32_e32 v0, v2, v0
	v_mul_f32_e32 v1, v3, v1
	v_lshlrev_b32_e32 v2, 16, v113
	v_and_b32_e32 v3, 0xffff0000, v113
	v_mul_f32_e32 v2, v4, v2
	v_mul_f32_e32 v3, v5, v3
	v_cvt_pk_bf16_f32 v0, v0, v1
	v_cvt_pk_bf16_f32 v1, v2, v3
	v_lshlrev_b32_e32 v2, 16, v6
	v_and_b32_e32 v3, 0xffff0000, v6
	v_mul_f32_e32 v4, v12, v34
	v_mul_f32_e32 v5, v13, v34
	s_mov_b64 s[2:3], 0x200
	v_mul_f32_e32 v2, v4, v2
	v_mul_f32_e32 v3, v5, v3
	v_lshlrev_b32_e32 v4, 16, v7
	v_and_b32_e32 v5, 0xffff0000, v7
	v_mul_f32_e32 v6, v14, v34
	v_mul_f32_e32 v7, v15, v34
	v_cvt_pk_bf16_f32 v2, v2, v3
	v_mul_f32_e32 v4, v6, v4
	v_mul_f32_e32 v5, v7, v5
	v_lshl_add_u64 v[32:33], v[36:37], 0, s[2:3]
	v_cvt_pk_bf16_f32 v3, v4, v5
	v_permlane32_swap_b32_e32 v0, v2
	s_nop 0
	v_permlane32_swap_b32_e32 v1, v3
	s_branch .LBB0_876
